# v55 + P0 rmsnorm: non-temporal hint on the x row loads (keep hbuf and w_in_t resident in the infinity cache for P1)
# speedup vs baseline: 1.0184x; 1.0046x over previous
.LBB0_117:
	global_load_dwordx4 v[28:31], v[16:17], off offset:-4096 nt
	global_load_dwordx4 v[32:35], v[16:17], off offset:-3072 nt
	global_load_dwordx4 v[36:39], v[16:17], off offset:-2048 nt
	global_load_dwordx4 v[40:43], v[16:17], off nt
	global_load_dwordx4 v[44:47], v[16:17], off offset:-1024 nt
	global_load_dwordx4 v[48:51], v[16:17], off offset:1024 nt
	global_load_dwordx4 v[2:5], v[16:17], off offset:3072 nt
	global_load_dwordx4 v[52:55], v[16:17], off offset:2048 nt
	s_add_i32 s3, s3, s88
	v_lshl_add_u64 v[16:17], v[16:17], 0, s[4:5]
	s_cmpk_gt_i32 s3, 0x7fff
	s_waitcnt vmcnt(7)
	v_mov_b32_e32 v62, v29
	s_waitcnt vmcnt(6)
	v_mov_b32_e32 v63, v33
	v_mov_b32_e32 v66, v31
	v_mov_b32_e32 v67, v35
	v_mov_b32_e32 v60, v28
	v_mov_b32_e32 v61, v32
	v_mov_b32_e32 v64, v30
	v_mov_b32_e32 v65, v34
	s_waitcnt vmcnt(5)
	v_pk_mul_f32 v[68:69], v[38:39], v[38:39]
	v_pk_mul_f32 v[70:71], v[36:37], v[36:37]
	v_pk_mul_f32 v[62:63], v[62:63], v[62:63]
	v_pk_mul_f32 v[66:67], v[66:67], v[66:67]
	v_pk_mov_b32 v[84:85], v[70:71], v[68:69] op_sel:[1,0]
	v_mov_b32_e32 v71, v69
	v_pk_fma_f32 v[60:61], v[60:61], v[60:61], v[62:63]
	v_pk_fma_f32 v[62:63], v[64:65], v[64:65], v[66:67]
	s_waitcnt vmcnt(3)
	v_mul_f32_e32 v72, v45, v45
	v_mul_f32_e32 v74, v47, v47
	v_pk_add_f32 v[64:65], v[84:85], v[70:71]
	v_pk_add_f32 v[60:61], v[60:61], v[62:63]
	v_mul_f32_e32 v27, v40, v40
	v_mul_f32_e32 v83, v41, v41
	v_mul_f32_e32 v86, v42, v42
	v_mul_f32_e32 v87, v43, v43
	v_pk_fma_f32 v[68:69], v[44:45], v[44:45], v[72:73] op_sel_hi:[1,1,0]
	v_pk_fma_f32 v[72:73], v[46:47], v[46:47], v[74:75] op_sel_hi:[1,1,0]
	v_pk_add_f32 v[62:63], v[64:65], v[64:65] op_sel:[0,1] op_sel_hi:[1,0]
	v_pk_add_f32 v[60:61], v[60:61], v[60:61] op_sel:[0,1] op_sel_hi:[1,0]
	s_waitcnt vmcnt(2)
	v_pk_mul_f32 v[76:77], v[50:51], v[50:51]
	v_pk_mul_f32 v[78:79], v[48:49], v[48:49]
	v_mov_b32_e32 v69, v86
	v_mov_b32_e32 v73, v87
	v_mov_b32_e32 v63, v83
	v_mov_b32_e32 v61, v27
	v_pk_mov_b32 v[74:75], v[78:79], v[76:77] op_sel:[1,0]
	v_mov_b32_e32 v79, v77
	v_pk_add_f32 v[64:65], v[68:69], v[72:73]
	v_pk_add_f32 v[60:61], v[60:61], v[62:63]
	s_waitcnt vmcnt(0)
	v_mul_f32_e32 v80, v53, v53
	v_mul_f32_e32 v82, v55, v55
	v_pk_add_f32 v[66:67], v[74:75], v[78:79]
	v_pk_add_f32 v[60:61], v[60:61], v[64:65]
	v_mul_f32_e32 v88, v2, v2
	v_mul_f32_e32 v89, v3, v3
	v_mul_f32_e32 v90, v4, v4
	v_mul_f32_e32 v91, v5, v5
	v_pk_fma_f32 v[76:77], v[52:53], v[52:53], v[80:81] op_sel_hi:[1,1,0]
	v_pk_fma_f32 v[80:81], v[54:55], v[54:55], v[82:83] op_sel_hi:[1,1,0]
	v_pk_add_f32 v[66:67], v[66:67], v[66:67] op_sel:[0,1] op_sel_hi:[1,0]
	v_pk_add_f32 v[60:61], v[60:61], v[60:61] op_sel:[0,1] op_sel_hi:[1,0]
	v_mov_b32_e32 v77, v90
	v_mov_b32_e32 v81, v91
	v_mov_b32_e32 v67, v89
	v_mov_b32_e32 v61, v88
	v_pk_add_f32 v[68:69], v[76:77], v[80:81]
	v_pk_add_f32 v[60:61], v[60:61], v[66:67]
	s_nop 0
	v_pk_add_f32 v[60:61], v[60:61], v[68:69]
	s_nop 0
	v_add_f32_e32 v27, v60, v61
	ds_bpermute_b32 v60, v20, v27
	s_waitcnt lgkmcnt(0)
	v_add_f32_e32 v27, v27, v60
	ds_bpermute_b32 v60, v21, v27
	s_waitcnt lgkmcnt(0)
	v_add_f32_e32 v27, v27, v60
	ds_bpermute_b32 v60, v22, v27
	s_waitcnt lgkmcnt(0)
	v_add_f32_e32 v27, v27, v60
	ds_bpermute_b32 v60, v23, v27
	s_waitcnt lgkmcnt(0)
	v_add_f32_e32 v27, v27, v60
	ds_bpermute_b32 v60, v24, v27
	s_waitcnt lgkmcnt(0)
	v_add_f32_e32 v27, v27, v60
	ds_bpermute_b32 v60, v25, v27
	s_waitcnt lgkmcnt(0)
	v_add_f32_e32 v27, v27, v60
	v_fmamk_f32 v27, v27, 0x3a000000, v26
	v_mul_f32_e32 v60, 0x4b800000, v27
	v_cmp_gt_f32_e32 vcc, s2, v27
	s_nop 1
	v_cndmask_b32_e32 v27, v27, v60, vcc
	v_rsq_f32_e32 v27, v27
	s_nop 0
	v_mul_f32_e32 v60, 0x45800000, v27
	v_cndmask_b32_e32 v27, v27, v60, vcc
	v_mul_f32_e32 v160, v28, v27
	v_mul_f32_e32 v161, v29, v27
	v_mul_f32_e32 v162, v30, v27
	v_mul_f32_e32 v163, v31, v27
	v_mul_f32_e32 v160, v92, v160
	v_mul_f32_e32 v161, v93, v161
	v_mul_f32_e32 v162, v94, v162
	v_mul_f32_e32 v163, v95, v163
	v_cvt_pk_bf16_f32 v164, v160, v161
	v_cvt_pk_bf16_f32 v165, v162, v163
	global_store_dwordx2 v[18:19], v[164:165], off
	v_mul_f32_e32 v168, v32, v27
	v_mul_f32_e32 v169, v33, v27
	v_mul_f32_e32 v170, v34, v27
	v_mul_f32_e32 v171, v35, v27
	v_mul_f32_e32 v168, v96, v168
	v_mul_f32_e32 v169, v97, v169
	v_mul_f32_e32 v170, v98, v170
	v_mul_f32_e32 v171, v99, v171
	v_cvt_pk_bf16_f32 v172, v168, v169
	v_cvt_pk_bf16_f32 v173, v170, v171
	global_store_dwordx2 v[18:19], v[172:173], off offset:512
	v_mul_f32_e32 v160, v36, v27
	v_mul_f32_e32 v161, v37, v27
	v_mul_f32_e32 v162, v38, v27
	v_mul_f32_e32 v163, v39, v27
	v_mul_f32_e32 v160, v100, v160
	v_mul_f32_e32 v161, v101, v161
	v_mul_f32_e32 v162, v102, v162
	v_mul_f32_e32 v163, v103, v163
	v_cvt_pk_bf16_f32 v164, v160, v161
	v_cvt_pk_bf16_f32 v165, v162, v163
	global_store_dwordx2 v[18:19], v[164:165], off offset:1024
	v_mul_f32_e32 v168, v44, v27
	v_mul_f32_e32 v169, v45, v27
	v_mul_f32_e32 v170, v46, v27
	v_mul_f32_e32 v171, v47, v27
	v_mul_f32_e32 v168, v104, v168
	v_mul_f32_e32 v169, v105, v169
	v_mul_f32_e32 v170, v106, v170
	v_mul_f32_e32 v171, v107, v171
	v_cvt_pk_bf16_f32 v172, v168, v169
	v_cvt_pk_bf16_f32 v173, v170, v171
	global_store_dwordx2 v[18:19], v[172:173], off offset:1536
	v_mul_f32_e32 v160, v40, v27
	v_mul_f32_e32 v161, v41, v27
	v_mul_f32_e32 v162, v42, v27
	v_mul_f32_e32 v163, v43, v27
	v_mul_f32_e32 v160, v108, v160
	v_mul_f32_e32 v161, v109, v161
	v_mul_f32_e32 v162, v110, v162
	v_mul_f32_e32 v163, v111, v163
	v_cvt_pk_bf16_f32 v164, v160, v161
	v_cvt_pk_bf16_f32 v165, v162, v163
	global_store_dwordx2 v[18:19], v[164:165], off offset:2048
	v_mul_f32_e32 v168, v48, v27
	v_mul_f32_e32 v169, v49, v27
	v_mul_f32_e32 v170, v50, v27
	v_mul_f32_e32 v171, v51, v27
	v_mul_f32_e32 v168, v118, v168
	v_mul_f32_e32 v169, v119, v169
	v_mul_f32_e32 v170, v120, v170
	v_mul_f32_e32 v171, v121, v171
	v_cvt_pk_bf16_f32 v172, v168, v169
	v_cvt_pk_bf16_f32 v173, v170, v171
	global_store_dwordx2 v[18:19], v[172:173], off offset:2560
	v_mul_f32_e32 v160, v52, v27
	v_mul_f32_e32 v161, v53, v27
	v_mul_f32_e32 v162, v54, v27
	v_mul_f32_e32 v163, v55, v27
	v_mul_f32_e32 v160, v122, v160
	v_mul_f32_e32 v161, v123, v161
	v_mul_f32_e32 v162, v124, v162
	v_mul_f32_e32 v163, v125, v163
	v_cvt_pk_bf16_f32 v164, v160, v161
	v_cvt_pk_bf16_f32 v165, v162, v163
	global_store_dwordx2 v[18:19], v[164:165], off offset:3072
	v_mul_f32_e32 v168, v2, v27
	v_mul_f32_e32 v169, v3, v27
	v_mul_f32_e32 v170, v4, v27
	v_mul_f32_e32 v171, v5, v27
	v_mul_f32_e32 v168, v126, v168
	v_mul_f32_e32 v169, v127, v169
	v_mul_f32_e32 v170, v128, v170
	v_mul_f32_e32 v171, v129, v171
	v_cvt_pk_bf16_f32 v172, v168, v169
	v_cvt_pk_bf16_f32 v173, v170, v171
	global_store_dwordx2 v[18:19], v[172:173], off offset:3584
	v_lshl_add_u64 v[18:19], v[18:19], 0, s[6:7]
	s_cbranch_scc0 .LBB0_117
